# LRS on top of LRG: LRU pass-A in-loop prefetch simplified to one pointer + 4 loads; scan step-2 prefix pairs read up front (no LDS latency in the dependent chain)
# baseline (speedup 1.0000x reference)
; #define LAS __attribute__((address_space(3)))
; __device__ __forceinline__ unsigned cvt_pk_bf16(float lo, float hi) { unsigned r; asm volatile("v_cvt_pk_bf16_f32 %0, %1, %2" : "=v"(r) : "v"(lo), "v"(hi)); return r; }
; __device__ __forceinline__ void lru_item(const Args& a, LAS unsigned char* lds, const int s, const int seg, const int hb, const int tid_in, const int lane_in, const int wave) {
;     ...
;     auto prefetch = [&](int k) {
;         const int t0 = tb + k * 64 + ct;
; #pragma unroll
;         for (int j = 0; j < 4; ++j) { const int tt = t0 + j - 3;
;             if (tt >= 0) xr[j] = *(const u32x4*)(XR + (size_t)(row0 + tt) * D + cch); else xr[j] = (u32x4){0u, 0u, 0u, 0u}; }
;     ...
;         { float xc[8];
; #pragma unroll
;           for (int i = 0; i < 8; ++i) xc[i] = cb[i];
; #pragma unroll
;           for (int j = 0; j < 4; ++j) { float xv[8]; const int tt = tb + k * 64 + ct + j - 3;
;               if (fin && tt < 0) { const float* sp = a.in[5] + ((size_t)(s - 1) * 3 + (tt + 3)) * D + cch; const f32x4 q0 = *(const f32x4*)sp, q1 = *(const f32x4*)(sp + 4);
; #pragma unroll
;                   for (int i = 0; i < 4; ++i) { xv[i] = q0[i]; xv[4 + i] = q1[i]; } }
;               else { const u32x4 w = xr[j];
;                   xv[0] = __uint_as_float(w.x << 16); xv[1] = __uint_as_float(w.x & 0xffff0000u); xv[2] = __uint_as_float(w.y << 16); xv[3] = __uint_as_float(w.y & 0xffff0000u);
;                   xv[4] = __uint_as_float(w.z << 16); xv[5] = __uint_as_float(w.z & 0xffff0000u); xv[6] = __uint_as_float(w.w << 16); xv[7] = __uint_as_float(w.w & 0xffff0000u); }
; #pragma unroll
;               for (int i = 0; i < 8; ++i) xc[i] += xv[i] * cw[j][i]; }
;           u32x4 pw; pw.x = cvt_pk_bf16(xc[0], xc[1]); pw.y = cvt_pk_bf16(xc[2], xc[3]); pw.z = cvt_pk_bf16(xc[4], xc[5]); pw.w = cvt_pk_bf16(xc[6], xc[7]);
;           *(LAS u32x4*)(xcb + ct * 72 + cg8 * 8) = pw;
;           *(LAS f32x4*)(xcf + ct * 68 + cg8 * 8) = (f32x4){xc[0], xc[1], xc[2], xc[3]}; *(LAS f32x4*)(xcf + ct * 68 + cg8 * 8 + 4) = (f32x4){xc[4], xc[5], xc[6], xc[7]}; }
;         bf16_t gcur[8];
; #pragma unroll
;         for (int i = 0; i < 8; ++i) gcur[i] = gt[i];
;         __syncthreads();
;         if (k + 1 < nch) prefetch(k + 1);
.LBB0_555:
	s_waitcnt vmcnt(16)
	v_lshlrev_b32_e32 v2, 16, v60
	v_and_b32_e32 v3, 0xffff0000, v60
	v_pk_fma_f32 v[2:3], v[12:13], v[2:3], v[16:17]
	v_lshlrev_b32_e32 v86, 16, v64
	v_and_b32_e32 v87, 0xffff0000, v64
	v_pk_fma_f32 v[2:3], v[20:21], v[86:87], v[2:3]
	v_lshlrev_b32_e32 v86, 16, v68
	v_and_b32_e32 v87, 0xffff0000, v68
	v_pk_fma_f32 v[2:3], v[28:29], v[86:87], v[2:3]
	v_lshlrev_b32_e32 v86, 16, v72
	v_and_b32_e32 v87, 0xffff0000, v72
	v_pk_fma_f32 v[86:87], v[36:37], v[86:87], v[2:3]
	v_lshlrev_b32_e32 v2, 16, v61
	v_and_b32_e32 v3, 0xffff0000, v61
	v_pk_fma_f32 v[2:3], v[14:15], v[2:3], v[18:19]
	v_lshlrev_b32_e32 v88, 16, v65
	v_and_b32_e32 v89, 0xffff0000, v65
	v_pk_fma_f32 v[2:3], v[22:23], v[88:89], v[2:3]
	v_lshlrev_b32_e32 v88, 16, v69
	v_and_b32_e32 v89, 0xffff0000, v69
	v_pk_fma_f32 v[2:3], v[30:31], v[88:89], v[2:3]
	v_lshlrev_b32_e32 v88, 16, v73
	v_and_b32_e32 v89, 0xffff0000, v73
	v_pk_fma_f32 v[88:89], v[38:39], v[88:89], v[2:3]
	v_lshlrev_b32_e32 v2, 16, v62
	v_and_b32_e32 v3, 0xffff0000, v62
	v_pk_fma_f32 v[2:3], v[4:5], v[2:3], v[8:9]
	v_lshlrev_b32_e32 v90, 16, v66
	v_and_b32_e32 v91, 0xffff0000, v66
	v_pk_fma_f32 v[2:3], v[24:25], v[90:91], v[2:3]
	v_lshlrev_b32_e32 v90, 16, v70
	v_and_b32_e32 v91, 0xffff0000, v70
	v_pk_fma_f32 v[2:3], v[32:33], v[90:91], v[2:3]
	v_lshlrev_b32_e32 v90, 16, v74
	v_and_b32_e32 v91, 0xffff0000, v74
	v_pk_fma_f32 v[90:91], v[40:41], v[90:91], v[2:3]
	v_lshlrev_b32_e32 v2, 16, v63
	v_and_b32_e32 v3, 0xffff0000, v63
	v_pk_fma_f32 v[2:3], v[6:7], v[2:3], v[10:11]
	v_lshlrev_b32_e32 v92, 16, v67
	v_and_b32_e32 v93, 0xffff0000, v67
	v_pk_fma_f32 v[2:3], v[26:27], v[92:93], v[2:3]
	v_lshlrev_b32_e32 v92, 16, v71
	v_and_b32_e32 v93, 0xffff0000, v71
	v_pk_fma_f32 v[2:3], v[34:35], v[92:93], v[2:3]
	v_lshlrev_b32_e32 v92, 16, v75
	v_and_b32_e32 v93, 0xffff0000, v75
	v_pk_fma_f32 v[92:93], v[42:43], v[92:93], v[2:3]
	v_cvt_pk_bf16_f32 v94, v86, v87
	v_cvt_pk_bf16_f32 v95, v88, v89
	v_cvt_pk_bf16_f32 v96, v90, v91
	s_cmp_lt_u32 s49, 15
	v_cvt_pk_bf16_f32 v97, v92, v93
	ds_write_b128 v118, v[94:97]
	ds_write_b128 v119, v[86:89] offset:9216
	ds_write_b128 v119, v[90:93] offset:9232
	s_waitcnt lgkmcnt(0)
	s_barrier
	s_cbranch_scc0 .LBB0_565
	v_add_u32_e32 v2, v76, v104
	v_mov_b32_e32 v3, v0
	v_lshlrev_b32_e32 v2, 11, v2
	v_add_u32_e32 v2, 0x1f800, v2
	v_lshl_add_u64 v[2:3], v[78:79], 0, v[2:3]
	global_load_dwordx4 v[60:63], v[2:3], off offset:-4096
	global_load_dwordx4 v[64:67], v[2:3], off offset:-2048
	global_load_dwordx4 v[68:71], v[2:3], off
	global_load_dwordx4 v[72:75], v[2:3], off offset:2048
.LBB0_565:
	ds_read_b128 v[86:89], v120
	ds_read_b128 v[90:93], v120 offset:64
	ds_read_b128 v[160:163], v122
	ds_read_b128 v[164:167], v122 offset:64
	ds_read_b32 v172, v121 offset:9216
	ds_read_b32 v173, v121 offset:9488
	ds_read_b32 v174, v121 offset:9760
	ds_read_b32 v175, v121 offset:10032
	ds_read_b32 v176, v123 offset:9216
	ds_read_b32 v177, v123 offset:9488
	ds_read_b32 v178, v123 offset:9760
	ds_read_b32 v179, v123 offset:10032
	s_waitcnt lgkmcnt(11)
	v_mfma_f32_16x16x32_bf16 v[94:97], v[86:89], v[44:47], 0
	s_waitcnt lgkmcnt(9)
	v_mfma_f32_16x16x32_bf16 v[168:171], v[160:163], v[44:47], 0
	v_mfma_f32_16x16x32_bf16 v[94:97], v[90:93], v[52:55], v[94:97]
	s_waitcnt lgkmcnt(8)
	v_mfma_f32_16x16x32_bf16 v[168:171], v[164:167], v[52:55], v[168:171]
	v_mfma_f32_16x16x32_bf16 v[86:89], v[86:89], v[48:51], 0
	v_mfma_f32_16x16x32_bf16 v[160:163], v[160:163], v[48:51], 0
	v_mfma_f32_16x16x32_bf16 v[86:89], v[90:93], v[56:59], v[86:89]
	v_mfma_f32_16x16x32_bf16 v[160:163], v[164:167], v[56:59], v[160:163]
	s_nop 7
	v_add_f32_e32 v94, v102, v94
	v_add_f32_e32 v95, v102, v95
	v_add_f32_e32 v96, v102, v96
	v_add_f32_e32 v97, v102, v97
	v_mul_f32_e32 v94, 0xbfb8aa3b, v94
	v_mul_f32_e32 v95, 0xbfb8aa3b, v95
	v_mul_f32_e32 v96, 0xbfb8aa3b, v96
	v_mul_f32_e32 v97, 0xbfb8aa3b, v97
	v_exp_f32_e32 v94, v94
	v_exp_f32_e32 v95, v95
	v_exp_f32_e32 v96, v96
	v_exp_f32_e32 v97, v97
	v_add_f32_e32 v86, v103, v86
	v_add_f32_e32 v87, v103, v87
	v_add_f32_e32 v88, v103, v88
	v_add_f32_e32 v89, v103, v89
	v_add_f32_e32 v94, 1.0, v94
	v_add_f32_e32 v95, 1.0, v95
	v_add_f32_e32 v96, 1.0, v96
	v_add_f32_e32 v97, 1.0, v97
	v_mul_f32_e32 v86, 0xbfb8aa3b, v86
	v_mul_f32_e32 v87, 0xbfb8aa3b, v87
	v_mul_f32_e32 v88, 0xbfb8aa3b, v88
	v_mul_f32_e32 v89, 0xbfb8aa3b, v89
	v_rcp_f32_e32 v94, v94
	v_rcp_f32_e32 v95, v95
	v_rcp_f32_e32 v96, v96
	v_rcp_f32_e32 v97, v97
	v_exp_f32_e32 v86, v86
	v_exp_f32_e32 v87, v87
	v_exp_f32_e32 v88, v88
	v_exp_f32_e32 v89, v89
	v_mul_f32_e32 v94, v105, v94
	v_mul_f32_e32 v95, v105, v95
	v_mul_f32_e32 v96, v105, v96
	v_mul_f32_e32 v97, v105, v97
	v_exp_f32_e32 v94, v94
	v_exp_f32_e32 v95, v95
	v_exp_f32_e32 v96, v96
	v_exp_f32_e32 v97, v97
	v_add_f32_e32 v86, 1.0, v86
	v_add_f32_e32 v87, 1.0, v87
	v_add_f32_e32 v88, 1.0, v88
	v_add_f32_e32 v89, 1.0, v89
	v_rcp_f32_e32 v86, v86
	v_rcp_f32_e32 v87, v87
	v_rcp_f32_e32 v88, v88
	v_rcp_f32_e32 v89, v89
	v_fma_f32 v180, -v94, v94, 1.0
	v_fma_f32 v181, -v95, v95, 1.0
	v_fma_f32 v182, -v96, v96, 1.0
	v_fma_f32 v183, -v97, v97, 1.0
	v_max_f32_e32 v180, 0, v180
	v_max_f32_e32 v181, 0, v181
	v_max_f32_e32 v182, 0, v182
	v_max_f32_e32 v183, 0, v183
	v_sqrt_f32_e32 v184, v180
	v_sqrt_f32_e32 v185, v181
	v_sqrt_f32_e32 v186, v182
	v_sqrt_f32_e32 v187, v183
	v_add_u32_e32 v188, -1, v184
	v_add_u32_e32 v189, -1, v185
	v_add_u32_e32 v190, -1, v186
	v_add_u32_e32 v191, -1, v187
	v_add_u32_e32 v98, 1, v184
	v_add_u32_e32 v99, 1, v185
	v_add_u32_e32 v100, 1, v186
	v_add_u32_e32 v101, 1, v187
	v_fma_f32 v1, -v188, v184, v180
	v_fma_f32 v2, -v189, v185, v181
	v_fma_f32 v3, -v190, v186, v182
	v_fma_f32 v126, -v191, v187, v183
	v_fma_f32 v180, -v98, v184, v180
	v_fma_f32 v181, -v99, v185, v181
	v_fma_f32 v182, -v100, v186, v182
	v_fma_f32 v183, -v101, v187, v183
	v_cmp_ge_f32_e64 vcc, 0, v1
	v_cmp_ge_f32_e64 s[0:1], 0, v2
	v_cmp_ge_f32_e64 s[82:83], 0, v3
	v_cndmask_b32_e64 v184, v184, v188, vcc
	v_cmp_ge_f32_e64 vcc, 0, v126
	v_cndmask_b32_e64 v185, v185, v189, s[0:1]
	v_cndmask_b32_e64 v186, v186, v190, s[82:83]
	v_cndmask_b32_e64 v187, v187, v191, vcc
	v_cmp_lt_f32_e64 s[0:1], 0, v180
	v_cmp_lt_f32_e64 s[82:83], 0, v181
	v_cmp_lt_f32_e64 vcc, 0, v182
	v_cndmask_b32_e64 v184, v184, v98, s[0:1]
	v_cmp_lt_f32_e64 s[0:1], 0, v183
	v_cndmask_b32_e64 v185, v185, v99, s[82:83]
	v_cndmask_b32_e64 v186, v186, v100, vcc
	v_cmp_ne_u32_e32 vcc, v116, v104
	v_cndmask_b32_e64 v187, v187, v101, s[0:1]
	v_mul_f32_e32 v87, v87, v185
	v_mul_f32_e32 v88, v88, v186
	v_cndmask_b32_e32 v184, 1.0, v184, vcc
	v_mul_f32_e32 v89, v89, v187
	s_waitcnt lgkmcnt(4)
; #define LAS __attribute__((address_space(3)))
; __device__ __forceinline__ float fast_sigmoid(float z) { return __builtin_amdgcn_rcpf(1.f + __builtin_amdgcn_exp2f(-z * L2E)); }
; __device__ __forceinline__ void lru_item(const Args& a, LAS unsigned char* lds, const int s, const int seg, const int hb, const int tid_in, const int lane_in, const int wave) {
;     ...
; #pragma unroll
;         for (int mi = 0; mi < 2; ++mi) { const int mt = mt0 + mi; f32x4 pr = {0.f, 0.f, 0.f, 0.f}, pi = {0.f, 0.f, 0.f, 0.f};
; #pragma unroll
;             for (int ks = 0; ks < 2; ++ks) { const bf16x8 af = *(const LAS bf16x8*)(xcb + (mt * 16 + fr) * 72 + ks * 32 + fq * 8);
;                 pr = __builtin_amdgcn_mfma_f32_16x16x32_bf16(af, brg[ks], pr, 0, 0, 0); pi = __builtin_amdgcn_mfma_f32_16x16x32_bf16(af, big[ks], pi, 0, 0, 0); }
; #pragma unroll
;             for (int i = 0; i < 4; ++i) { const int t = mt * 16 + 4 * fq + i;
;                 const float r = fast_sigmoid(pr[i] + e_brg), ig = fast_sigmoid(pi[i] + e_big);
;                 const float av = __builtin_amdgcn_exp2f(r * e_ls);
;                 float mult = sqrtf(fmaxf(1.f - av * av, 0.f));
;                 if (!fin && tb + k * 64 + t == 0) mult = 1.f;
;                 const float xcv = xcf[t * 68 + jt * 16 + fr];
;                 LA[t * 64 + jt * 16 + fr] = av; LB[t * 64 + jt * 16 + fr] = mult * ig * xcv; } }
;         __syncthreads();
;         float av[8], bv[8];
;         { float Ap = 1.f, Bp = 0.f;
; #pragma unroll
;           for (int i = 0; i < 8; ++i) { av[i] = LA[(sseg * 8 + i) * 64 + sj]; bv[i] = LB[(sseg * 8 + i) * 64 + sj]; Bp = av[i] * Bp + bv[i]; Ap *= av[i]; }
;           SA[sseg * 64 + sj] = Ap; SB[sseg * 64 + sj] = Bp; }
;         __syncthreads();
;         { float hv = HC[(k & 1) * 64 + sj], pv = PC[(k & 1) * 64 + sj];
	v_mul_f32_e32 v86, v86, v184
	v_mul_f32_e32 v87, v173, v87
	v_mul_f32_e32 v88, v174, v88
	v_mul_f32_e32 v89, v175, v89
	v_mul_f32_e32 v86, v172, v86
	ds_write2st64_b32 v108, v95, v87 offset0:104 offset1:168
	ds_write2st64_b32 v109, v96, v88 offset0:104 offset1:168
	ds_write2st64_b32 v110, v97, v89 offset0:104 offset1:168
	ds_write2st64_b32 v107, v94, v86 offset0:104 offset1:168
	v_add_f32_e32 v168, v102, v168
	v_add_f32_e32 v169, v102, v169
	v_add_f32_e32 v170, v102, v170
	v_add_f32_e32 v171, v102, v171
	v_mul_f32_e32 v168, 0xbfb8aa3b, v168
	v_mul_f32_e32 v169, 0xbfb8aa3b, v169
	v_mul_f32_e32 v170, 0xbfb8aa3b, v170
	v_mul_f32_e32 v171, 0xbfb8aa3b, v171
	v_exp_f32_e32 v168, v168
	v_exp_f32_e32 v169, v169
	v_exp_f32_e32 v170, v170
	v_exp_f32_e32 v171, v171
	v_add_f32_e32 v160, v103, v160
	v_add_f32_e32 v161, v103, v161
	v_add_f32_e32 v162, v103, v162
	v_add_f32_e32 v163, v103, v163
	v_add_f32_e32 v168, 1.0, v168
	v_add_f32_e32 v169, 1.0, v169
	v_add_f32_e32 v170, 1.0, v170
	v_add_f32_e32 v171, 1.0, v171
	v_mul_f32_e32 v160, 0xbfb8aa3b, v160
	v_mul_f32_e32 v161, 0xbfb8aa3b, v161
	v_mul_f32_e32 v162, 0xbfb8aa3b, v162
	v_mul_f32_e32 v163, 0xbfb8aa3b, v163
	v_rcp_f32_e32 v168, v168
	v_rcp_f32_e32 v169, v169
	v_rcp_f32_e32 v170, v170
	v_rcp_f32_e32 v171, v171
	v_exp_f32_e32 v160, v160
	v_exp_f32_e32 v161, v161
	v_exp_f32_e32 v162, v162
	v_exp_f32_e32 v163, v163
	v_mul_f32_e32 v168, v105, v168
	v_mul_f32_e32 v169, v105, v169
	v_mul_f32_e32 v170, v105, v170
	v_mul_f32_e32 v171, v105, v171
	v_exp_f32_e32 v168, v168
	v_exp_f32_e32 v169, v169
	v_exp_f32_e32 v170, v170
	v_exp_f32_e32 v171, v171
	v_add_f32_e32 v160, 1.0, v160
	v_add_f32_e32 v161, 1.0, v161
	v_add_f32_e32 v162, 1.0, v162
	v_add_f32_e32 v163, 1.0, v163
	v_rcp_f32_e32 v160, v160
	v_rcp_f32_e32 v161, v161
	v_rcp_f32_e32 v162, v162
	v_rcp_f32_e32 v163, v163
	v_fma_f32 v180, -v168, v168, 1.0
	v_fma_f32 v181, -v169, v169, 1.0
	v_fma_f32 v182, -v170, v170, 1.0
	v_fma_f32 v183, -v171, v171, 1.0
	v_max_f32_e32 v180, 0, v180
	v_max_f32_e32 v181, 0, v181
	v_max_f32_e32 v182, 0, v182
	v_max_f32_e32 v183, 0, v183
	v_sqrt_f32_e32 v184, v180
	v_sqrt_f32_e32 v185, v181
	v_sqrt_f32_e32 v186, v182
	v_sqrt_f32_e32 v187, v183
	v_add_u32_e32 v188, -1, v184
	v_add_u32_e32 v189, -1, v185
	v_add_u32_e32 v190, -1, v186
	v_add_u32_e32 v191, -1, v187
	v_add_u32_e32 v98, 1, v184
	v_add_u32_e32 v99, 1, v185
	v_add_u32_e32 v100, 1, v186
	v_add_u32_e32 v101, 1, v187
	v_fma_f32 v1, -v188, v184, v180
	v_fma_f32 v2, -v189, v185, v181
	v_fma_f32 v3, -v190, v186, v182
	v_fma_f32 v126, -v191, v187, v183
	v_fma_f32 v180, -v98, v184, v180
	v_fma_f32 v181, -v99, v185, v181
	v_fma_f32 v182, -v100, v186, v182
	v_fma_f32 v183, -v101, v187, v183
	v_cmp_ge_f32_e64 vcc, 0, v1
	v_cmp_ge_f32_e64 s[0:1], 0, v2
	v_cmp_ge_f32_e64 s[82:83], 0, v3
	v_cndmask_b32_e64 v184, v184, v188, vcc
	v_cmp_ge_f32_e64 vcc, 0, v126
	v_cndmask_b32_e64 v185, v185, v189, s[0:1]
	v_cndmask_b32_e64 v186, v186, v190, s[82:83]
	v_cndmask_b32_e64 v187, v187, v191, vcc
	v_cmp_lt_f32_e64 s[0:1], 0, v180
	v_cmp_lt_f32_e64 s[82:83], 0, v181
	v_cmp_lt_f32_e64 vcc, 0, v182
	v_cndmask_b32_e64 v184, v184, v98, s[0:1]
	v_cmp_lt_f32_e64 s[0:1], 0, v183
	v_cndmask_b32_e64 v185, v185, v99, s[82:83]
	v_cndmask_b32_e64 v186, v186, v100, vcc
	v_cmp_ne_u32_e32 vcc, v117, v104
	v_cndmask_b32_e64 v187, v187, v101, s[0:1]
	v_mul_f32_e32 v161, v161, v185
	v_mul_f32_e32 v162, v162, v186
	v_cndmask_b32_e32 v184, 1.0, v184, vcc
	v_mul_f32_e32 v163, v163, v187
	s_waitcnt lgkmcnt(0)
	v_mul_f32_e32 v160, v160, v184
	v_mul_f32_e32 v161, v177, v161
	v_mul_f32_e32 v162, v178, v162
	v_mul_f32_e32 v163, v179, v163
	v_mul_f32_e32 v160, v176, v160
	ds_write2st64_b32 v112, v169, v161 offset0:104 offset1:168
	ds_write2st64_b32 v113, v170, v162 offset0:104 offset1:168
	ds_write2st64_b32 v114, v171, v163 offset0:104 offset1:168
	ds_write2st64_b32 v111, v168, v160 offset0:104 offset1:168
	s_waitcnt lgkmcnt(0)
	s_barrier
	ds_read2st64_b32 v[96:97], v124 offset0:168 offset1:169
	ds_read2st64_b32 v[98:99], v124 offset0:104 offset1:105
	ds_read2st64_b32 v[92:93], v124 offset0:106 offset1:107
	ds_read2st64_b32 v[88:89], v124 offset0:108 offset1:109
	ds_read2st64_b32 v[86:87], v124 offset0:110 offset1:111
	ds_read2st64_b32 v[94:95], v124 offset0:170 offset1:171
	ds_read2st64_b32 v[90:91], v124 offset0:172 offset1:173
	ds_read2st64_b32 v[2:3], v124 offset0:174 offset1:175
	s_waitcnt lgkmcnt(6)
	v_fma_f32 v1, 0, v98, v96
	v_fma_f32 v1, v1, v99, v97
	v_mul_f32_e32 v100, v98, v99
	s_waitcnt lgkmcnt(2)
	v_fma_f32 v1, v1, v92, v94
	v_mul_f32_e32 v100, v100, v92
	v_fma_f32 v1, v1, v93, v95
	v_mul_f32_e32 v100, v100, v93
	s_waitcnt lgkmcnt(1)
	v_fma_f32 v1, v1, v88, v90
	v_mul_f32_e32 v100, v100, v88
	v_fma_f32 v1, v1, v89, v91
	v_mul_f32_e32 v100, v100, v89
	s_waitcnt lgkmcnt(0)
	v_fma_f32 v1, v1, v86, v2
	v_mul_f32_e32 v100, v100, v86
	v_fma_f32 v1, v1, v87, v3
	v_mul_f32_e32 v100, v100, v87
	ds_write2st64_b32 v125, v100, v1 offset0:232 offset1:240
	v_and_or_b32 v1, v104, 64, v77
	v_lshl_add_u32 v1, v1, 2, 0
	s_waitcnt lgkmcnt(0)
	s_barrier
; __device__ __forceinline__ unsigned cvt_pk_bf16(float lo, float hi) { unsigned r; asm volatile("v_cvt_pk_bf16_f32 %0, %1, %2" : "=v"(r) : "v"(lo), "v"(hi)); return r; }
; __device__ __forceinline__ void lru_item(const Args& a, LAS unsigned char* lds, const int s, const int seg, const int hb, const int tid_in, const int lane_in, const int wave) {
;     ...
;         { float hv = HC[(k & 1) * 64 + sj], pv = PC[(k & 1) * 64 + sj];
; #pragma unroll
;           for (int q = 0; q < 8; ++q) { const float A_ = SA[q * 64 + sj], B_ = SB[q * 64 + sj]; if (q < sseg) { hv = A_ * hv + B_; pv *= A_; } }
;           const size_t ob = (size_t)(row0 + tb + k * 64 + sseg * 8) * D + c0 + sj;
; #pragma unroll
;           for (int i = 0; i < 8; ++i) { hv = av[i] * hv + bv[i]; pv *= av[i];
;               if (fin) { const float g = __uint_as_float((unsigned)gcur[i] << 16); YL[(size_t)(row0 + tb + k * 64 + sseg * 8 + i) * (2 * D) + c0 + sj] = (bf16_t)(cvt_pk_bf16(hv * g, 0.f) & 0xffffu); }
;               else { const unsigned w = cvt_pk_bf16(hv, pv); HL[ob + (size_t)i * D] = (bf16_t)(w & 0xffffu); PB[ob + (size_t)i * D] = (bf16_t)(w >> 16); } }
;           if (sseg == 7) { HC[((k + 1) & 1) * 64 + sj] = hv; PC[((k + 1) & 1) * 64 + sj] = pv;
;               if (k + 1 == nch) { if (fin) a.out[O_HS + (size_t)(s - 1) * D + c0 + sj] = hv;
;                   else { float* ag = (float*)(ws + WS_AGG) + (size_t)seg * 2048 + c0 + sj; ag[0] = pv; ag[1024] = hv; } } } }
	ds_read2st64_b32 v[100:101], v1 offset0:248 offset1:250
	ds_read2st64_b32 v[160:161], v106 offset0:232 offset1:240
	ds_read2st64_b32 v[162:163], v106 offset0:233 offset1:241
	ds_read2st64_b32 v[164:165], v106 offset0:234 offset1:242
	ds_read2st64_b32 v[166:167], v106 offset0:235 offset1:243
	ds_read2st64_b32 v[168:169], v106 offset0:236 offset1:244
	ds_read2st64_b32 v[170:171], v106 offset0:237 offset1:245
	ds_read2st64_b32 v[172:173], v106 offset0:238 offset1:246
	ds_read2st64_b32 v[174:175], v106 offset0:239 offset1:247
	s_mov_b64 s[0:1], exec
	s_waitcnt lgkmcnt(0)
	s_and_b64 exec, s[0:1], s[4:5]
	v_fma_f32 v100, v100, v160, v161
	v_mul_f32_e32 v101, v101, v160
	s_and_b64 exec, s[0:1], s[6:7]
	v_fma_f32 v100, v100, v162, v163
	v_mul_f32_e32 v101, v101, v162
	s_and_b64 exec, s[0:1], s[8:9]
	v_fma_f32 v100, v100, v164, v165
	v_mul_f32_e32 v101, v101, v164
	s_and_b64 exec, s[0:1], s[10:11]
	v_fma_f32 v100, v100, v166, v167
	v_mul_f32_e32 v101, v101, v166
	s_and_b64 exec, s[0:1], s[12:13]
	v_fma_f32 v100, v100, v168, v169
	v_mul_f32_e32 v101, v101, v168
	s_and_b64 exec, s[0:1], s[14:15]
	v_fma_f32 v100, v100, v170, v171
	v_mul_f32_e32 v101, v101, v170
	s_and_b64 exec, s[0:1], s[16:17]
	v_fma_f32 v100, v100, v172, v173
	v_mul_f32_e32 v101, v101, v172
	s_and_b64 exec, s[0:1], s[18:19]
	v_fma_f32 v100, v100, v174, v175
	v_mul_f32_e32 v101, v101, v174
	s_mov_b64 exec, s[0:1]
	v_add_u32_e32 v128, v115, v104
	v_ashrrev_i32_e32 v129, 31, v128
	s_waitcnt lgkmcnt(0)
	v_fma_f32 v1, v98, v100, v96
	v_mul_f32_e32 v96, v98, v101
	v_lshlrev_b64 v[100:101], 11, v[128:129]
	v_lshl_or_b32 v100, v84, 1, v100
	v_lshl_add_u64 v[128:129], s[26:27], 0, v[100:101]
	v_lshl_add_u64 v[100:101], s[28:29], 0, v[100:101]
	v_cvt_pk_bf16_f32 v98, v1, v96
	global_store_short v[128:129], v98, off
	global_store_short_d16_hi v[100:101], v98, off
	v_fmac_f32_e32 v97, v99, v1
	v_mul_f32_e32 v1, v99, v96
	v_cvt_pk_bf16_f32 v96, v97, v1
	global_store_short v[128:129], v96, off offset:2048
	global_store_short_d16_hi v[100:101], v96, off offset:2048
	v_add_co_u32_e32 v96, vcc, s94, v128
	v_fma_f32 v94, v92, v97, v94
	s_nop 0
	v_addc_co_u32_e32 v97, vcc, 0, v129, vcc
	v_add_co_u32_e32 v98, vcc, s95, v128
	v_mul_f32_e32 v1, v92, v1
	s_nop 0
	v_addc_co_u32_e32 v99, vcc, 0, v129, vcc
	v_add_co_u32_e32 v140, vcc, s94, v100
	v_cvt_pk_bf16_f32 v92, v94, v1
	global_store_short v[98:99], v92, off offset:-4096
	s_nop 0
	v_addc_co_u32_e32 v141, vcc, 0, v101, vcc
	v_add_co_u32_e32 v142, vcc, s95, v100
	v_fmac_f32_e32 v95, v93, v94
	s_nop 0
	v_addc_co_u32_e32 v143, vcc, 0, v101, vcc
	global_store_short_d16_hi v[142:143], v92, off offset:-4096
	v_mul_f32_e32 v1, v93, v1
	v_cvt_pk_bf16_f32 v92, v95, v1
	global_store_short v[96:97], v92, off offset:2048
	global_store_short_d16_hi v[140:141], v92, off offset:2048
	v_fma_f32 v90, v88, v95, v90
	v_mul_f32_e32 v1, v88, v1
	v_cvt_pk_bf16_f32 v88, v90, v1
	global_store_short v[98:99], v88, off
	global_store_short_d16_hi v[142:143], v88, off
	v_fmac_f32_e32 v91, v89, v90
	v_mul_f32_e32 v1, v89, v1
	v_cvt_pk_bf16_f32 v88, v91, v1
	s_movk_i32 s0, 0x3000
	global_store_short v[98:99], v88, off offset:2048
	global_store_short_d16_hi v[142:143], v88, off offset:2048
	v_add_co_u32_e32 v88, vcc, s0, v128
	v_fma_f32 v2, v86, v91, v2
	s_nop 0
	v_addc_co_u32_e32 v89, vcc, 0, v129, vcc
	v_add_co_u32_e32 v90, vcc, 0x3000, v100
	v_mul_f32_e32 v1, v86, v1
	s_nop 0
	v_addc_co_u32_e32 v91, vcc, 0, v101, vcc
	v_cvt_pk_bf16_f32 v86, v2, v1
	global_store_short v[88:89], v86, off
	global_store_short_d16_hi v[90:91], v86, off
	v_fmac_f32_e32 v3, v87, v2
	v_mul_f32_e32 v2, v87, v1
	v_cvt_pk_bf16_f32 v1, v3, v2
	s_mov_b64 s[96:97], -1
	s_mov_b64 s[0:1], 0
	global_store_short v[88:89], v1, off offset:2048
	global_store_short_d16_hi v[90:91], v1, off offset:2048
	s_and_saveexec_b64 vcc, s[2:3]
	s_cbranch_execz .LBB0_586
	v_add_u32_e32 v1, 64, v104
	v_and_b32_e32 v86, 64, v1
	v_lshl_add_u32 v86, v86, 2, v106
	s_cmp_eq_u32 s49, 15
	ds_write2st64_b32 v86, v3, v2 offset0:248 offset1:250
	s_cbranch_scc0 .LBB0_584
	global_store_dword v[80:81], v2, off
	global_store_dword v[82:83], v3, off
	s_branch .LBB0_585
